# v32
# baseline (speedup 1.0000x reference)
.LBB0_219:
	ds_read_b128 v[164:167], v160
	ds_read_b128 v[168:171], v160 offset:1024
	ds_read_b128 v[172:175], v160 offset:2048
	ds_read_b128 v[176:179], v160 offset:3072
	v_lshl_add_u64 v[240:241], v[144:145], 0, s[6:7]
	s_add_i32 m0, s100, 0xbf80
	ds_read_b128 v[184:187], v152
	ds_read_b128 v[190:193], v152 offset:1024
	ds_read_b128 v[194:197], v151
	ds_read_b128 v[198:201], v151 offset:1024
	ds_read_b128 v[206:209], v150
	ds_read_b128 v[212:215], v150 offset:1024
	ds_read_b128 v[216:219], v149
	ds_read_b128 v[220:223], v149 offset:1024
	global_load_lds_dwordx4 v[240:241], off offset:128
	s_add_i32 m0, s100, 0xdf80
	v_lshl_add_u64 v[242:243], v[142:143], 0, s[6:7]
	global_load_lds_dwordx4 v[242:243], off offset:128
	s_waitcnt lgkmcnt(8)
	s_barrier
	s_waitcnt lgkmcnt(0)
	v_mfma_f32_16x16x32_bf16 v[124:127], v[184:187], v[164:167], v[124:127]
	v_mfma_f32_16x16x32_bf16 v[120:123], v[184:187], v[172:175], v[120:123]
	v_mfma_f32_16x16x32_bf16 v[116:119], v[194:197], v[164:167], v[116:119]
	v_mfma_f32_16x16x32_bf16 v[112:115], v[194:197], v[172:175], v[112:115]
	v_mfma_f32_16x16x32_bf16 v[108:111], v[206:209], v[164:167], v[108:111]
	v_mfma_f32_16x16x32_bf16 v[104:107], v[206:209], v[172:175], v[104:107]
	v_mfma_f32_16x16x32_bf16 v[100:103], v[216:219], v[164:167], v[100:103]
	v_mfma_f32_16x16x32_bf16 v[96:99], v[216:219], v[172:175], v[96:99]
	v_mfma_f32_16x16x32_bf16 v[124:127], v[190:193], v[168:171], v[124:127]
	v_mfma_f32_16x16x32_bf16 v[120:123], v[190:193], v[176:179], v[120:123]
	v_mfma_f32_16x16x32_bf16 v[116:119], v[198:201], v[168:171], v[116:119]
	v_mfma_f32_16x16x32_bf16 v[112:115], v[198:201], v[176:179], v[112:115]
	v_mfma_f32_16x16x32_bf16 v[108:111], v[212:215], v[168:171], v[108:111]
	v_mfma_f32_16x16x32_bf16 v[104:107], v[212:215], v[176:179], v[104:107]
	v_mfma_f32_16x16x32_bf16 v[100:103], v[220:223], v[168:171], v[100:103]
	v_mfma_f32_16x16x32_bf16 v[96:99], v[220:223], v[176:179], v[96:99]
	s_barrier
	v_lshl_add_u64 v[244:245], v[130:131], 0, s[6:7]
	s_add_i32 m0, s101, 0xff00
	ds_read_b128 v[224:227], v159
	ds_read_b128 v[228:231], v159 offset:1024
	ds_read_b128 v[232:235], v159 offset:2048
	ds_read_b128 v[236:239], v159 offset:3072
	global_load_lds_dwordx4 v[244:245], off offset:256
	v_lshl_add_u64 v[246:247], v[132:133], 0, s[6:7]
	s_add_i32 m0, m0, 0x2000
	s_add_i32 s11, s11, 2
	global_load_lds_dwordx4 v[246:247], off offset:256
	s_barrier
	s_waitcnt lgkmcnt(0)
	v_mfma_f32_16x16x32_bf16 v[92:95], v[184:187], v[224:227], v[92:95]
	v_mfma_f32_16x16x32_bf16 v[88:91], v[184:187], v[232:235], v[88:91]
	v_mfma_f32_16x16x32_bf16 v[84:87], v[194:197], v[224:227], v[84:87]
	v_mfma_f32_16x16x32_bf16 v[80:83], v[194:197], v[232:235], v[80:83]
	v_mfma_f32_16x16x32_bf16 v[76:79], v[206:209], v[224:227], v[76:79]
	v_mfma_f32_16x16x32_bf16 v[72:75], v[206:209], v[232:235], v[72:75]
	v_mfma_f32_16x16x32_bf16 v[68:71], v[216:219], v[224:227], v[68:71]
	v_mfma_f32_16x16x32_bf16 v[64:67], v[216:219], v[232:235], v[64:67]
	v_mfma_f32_16x16x32_bf16 v[92:95], v[190:193], v[228:231], v[92:95]
	v_mfma_f32_16x16x32_bf16 v[88:91], v[190:193], v[236:239], v[88:91]
	v_mfma_f32_16x16x32_bf16 v[84:87], v[198:201], v[228:231], v[84:87]
	v_mfma_f32_16x16x32_bf16 v[80:83], v[198:201], v[236:239], v[80:83]
	v_mfma_f32_16x16x32_bf16 v[76:79], v[212:215], v[228:231], v[76:79]
	v_mfma_f32_16x16x32_bf16 v[72:75], v[212:215], v[236:239], v[72:75]
	v_mfma_f32_16x16x32_bf16 v[68:71], v[220:223], v[228:231], v[68:71]
	v_mfma_f32_16x16x32_bf16 v[64:67], v[220:223], v[236:239], v[64:67]
	v_lshl_add_u64 v[248:249], v[134:135], 0, s[6:7]
	v_lshl_add_u64 v[250:251], v[248:249], 0, s[64:65]
	s_mov_b32 m0, s100
	s_barrier
	ds_read_b128 v[184:187], v152 offset:16384
	ds_read_b128 v[190:193], v152 offset:17408
	ds_read_b128 v[194:197], v151 offset:16384
	ds_read_b128 v[198:201], v151 offset:17408
	ds_read_b128 v[206:209], v150 offset:16384
	ds_read_b128 v[212:215], v150 offset:17408
	ds_read_b128 v[216:219], v149 offset:16384
	ds_read_b128 v[220:223], v149 offset:17408
	global_load_lds_dwordx4 v[250:251], off
	s_add_i32 m0, s100, 0x1f00
	v_lshl_add_u64 v[250:251], v[136:137], 0, s[6:7]
	global_load_lds_dwordx4 v[250:251], off offset:256
	s_barrier
	s_waitcnt lgkmcnt(0)
	v_mfma_f32_16x16x32_bf16 v[60:63], v[184:187], v[164:167], v[60:63]
	v_mfma_f32_16x16x32_bf16 v[56:59], v[184:187], v[172:175], v[56:59]
	v_mfma_f32_16x16x32_bf16 v[52:55], v[194:197], v[164:167], v[52:55]
	v_mfma_f32_16x16x32_bf16 v[48:51], v[194:197], v[172:175], v[48:51]
	v_mfma_f32_16x16x32_bf16 v[44:47], v[206:209], v[164:167], v[44:47]
	v_mfma_f32_16x16x32_bf16 v[40:43], v[206:209], v[172:175], v[40:43]
	v_mfma_f32_16x16x32_bf16 v[36:39], v[216:219], v[164:167], v[36:39]
	v_mfma_f32_16x16x32_bf16 v[32:35], v[216:219], v[172:175], v[32:35]
	v_mfma_f32_16x16x32_bf16 v[60:63], v[190:193], v[168:171], v[60:63]
	v_mfma_f32_16x16x32_bf16 v[56:59], v[190:193], v[176:179], v[56:59]
	v_mfma_f32_16x16x32_bf16 v[52:55], v[198:201], v[168:171], v[52:55]
	v_mfma_f32_16x16x32_bf16 v[48:51], v[198:201], v[176:179], v[48:51]
	v_mfma_f32_16x16x32_bf16 v[44:47], v[212:215], v[168:171], v[44:47]
	v_mfma_f32_16x16x32_bf16 v[40:43], v[212:215], v[176:179], v[40:43]
	v_mfma_f32_16x16x32_bf16 v[36:39], v[220:223], v[168:171], v[36:39]
	v_mfma_f32_16x16x32_bf16 v[32:35], v[220:223], v[176:179], v[32:35]
	s_barrier
	v_lshl_add_u64 v[252:253], v[140:141], 0, s[6:7]
	s_add_i32 m0, s101, 0x13f00
	global_load_lds_dwordx4 v[252:253], off offset:256
	s_add_i32 m0, m0, 0x2000
	v_lshl_add_u64 v[188:189], v[138:139], 0, s[6:7]
	global_load_lds_dwordx4 v[188:189], off offset:256
	s_waitcnt vmcnt(6)
	s_barrier
	v_mfma_f32_16x16x32_bf16 v[28:31], v[184:187], v[224:227], v[28:31]
	v_mfma_f32_16x16x32_bf16 v[24:27], v[184:187], v[232:235], v[24:27]
	v_mfma_f32_16x16x32_bf16 v[20:23], v[194:197], v[224:227], v[20:23]
	v_mfma_f32_16x16x32_bf16 v[16:19], v[194:197], v[232:235], v[16:19]
	v_mfma_f32_16x16x32_bf16 v[12:15], v[206:209], v[224:227], v[12:15]
	v_mfma_f32_16x16x32_bf16 v[8:11], v[206:209], v[232:235], v[8:11]
	v_mfma_f32_16x16x32_bf16 v[4:7], v[216:219], v[224:227], v[4:7]
	v_mfma_f32_16x16x32_bf16 v[0:3], v[216:219], v[232:235], v[0:3]
	v_mfma_f32_16x16x32_bf16 v[28:31], v[190:193], v[228:231], v[28:31]
	v_mfma_f32_16x16x32_bf16 v[24:27], v[190:193], v[236:239], v[24:27]
	v_mfma_f32_16x16x32_bf16 v[20:23], v[198:201], v[228:231], v[20:23]
	v_mfma_f32_16x16x32_bf16 v[16:19], v[198:201], v[236:239], v[16:19]
	v_mfma_f32_16x16x32_bf16 v[12:15], v[212:215], v[228:231], v[12:15]
	v_mfma_f32_16x16x32_bf16 v[8:11], v[212:215], v[236:239], v[8:11]
	v_mfma_f32_16x16x32_bf16 v[4:7], v[220:223], v[228:231], v[4:7]
	v_mfma_f32_16x16x32_bf16 v[0:3], v[220:223], v[236:239], v[0:3]
	s_barrier
	ds_read_b128 v[164:167], v155
	ds_read_b128 v[168:171], v155 offset:1024
	ds_read_b128 v[172:175], v155 offset:2048
	ds_read_b128 v[176:179], v155 offset:3072
	s_add_i32 m0, s100, 0x3f00
	ds_read_b128 v[184:187], v152 offset:32768
	ds_read_b128 v[190:193], v152 offset:33792
	ds_read_b128 v[194:197], v151 offset:32768
	ds_read_b128 v[198:201], v151 offset:33792
	ds_read_b128 v[206:209], v150 offset:32768
	ds_read_b128 v[212:215], v150 offset:33792
	ds_read_b128 v[216:219], v149 offset:32768
	global_load_lds_dwordx4 v[240:241], off offset:256
	s_add_i32 m0, s100, 0x5f00
	ds_read_b128 v[220:223], v149 offset:33792
	global_load_lds_dwordx4 v[242:243], off offset:256
	s_waitcnt lgkmcnt(8)
	s_barrier
	s_waitcnt lgkmcnt(0)
	v_mfma_f32_16x16x32_bf16 v[124:127], v[184:187], v[164:167], v[124:127]
	v_mfma_f32_16x16x32_bf16 v[120:123], v[184:187], v[172:175], v[120:123]
	v_mfma_f32_16x16x32_bf16 v[116:119], v[194:197], v[164:167], v[116:119]
	v_mfma_f32_16x16x32_bf16 v[112:115], v[194:197], v[172:175], v[112:115]
	v_mfma_f32_16x16x32_bf16 v[108:111], v[206:209], v[164:167], v[108:111]
	v_mfma_f32_16x16x32_bf16 v[104:107], v[206:209], v[172:175], v[104:107]
	v_mfma_f32_16x16x32_bf16 v[100:103], v[216:219], v[164:167], v[100:103]
	v_mfma_f32_16x16x32_bf16 v[96:99], v[216:219], v[172:175], v[96:99]
	v_mfma_f32_16x16x32_bf16 v[124:127], v[190:193], v[168:171], v[124:127]
	v_mfma_f32_16x16x32_bf16 v[120:123], v[190:193], v[176:179], v[120:123]
	v_mfma_f32_16x16x32_bf16 v[116:119], v[198:201], v[168:171], v[116:119]
	v_mfma_f32_16x16x32_bf16 v[112:115], v[198:201], v[176:179], v[112:115]
	v_mfma_f32_16x16x32_bf16 v[108:111], v[212:215], v[168:171], v[108:111]
	v_mfma_f32_16x16x32_bf16 v[104:107], v[212:215], v[176:179], v[104:107]
	v_mfma_f32_16x16x32_bf16 v[100:103], v[220:223], v[168:171], v[100:103]
	v_mfma_f32_16x16x32_bf16 v[96:99], v[220:223], v[176:179], v[96:99]
	s_barrier
	s_add_i32 m0, s101, 0x17e80
	ds_read_b128 v[224:227], v153
	ds_read_b128 v[228:231], v153 offset:1024
	ds_read_b128 v[232:235], v153 offset:2048
	global_load_lds_dwordx4 v[244:245], off offset:384
	s_add_i32 m0, m0, 0x2000
	ds_read_b128 v[236:239], v153 offset:3072
	global_load_lds_dwordx4 v[246:247], off offset:384
	s_barrier
	s_waitcnt lgkmcnt(0)
	v_mfma_f32_16x16x32_bf16 v[92:95], v[184:187], v[224:227], v[92:95]
	v_mfma_f32_16x16x32_bf16 v[88:91], v[184:187], v[232:235], v[88:91]
	v_mfma_f32_16x16x32_bf16 v[84:87], v[194:197], v[224:227], v[84:87]
	v_mfma_f32_16x16x32_bf16 v[80:83], v[194:197], v[232:235], v[80:83]
	v_mfma_f32_16x16x32_bf16 v[76:79], v[206:209], v[224:227], v[76:79]
	v_mfma_f32_16x16x32_bf16 v[72:75], v[206:209], v[232:235], v[72:75]
	v_mfma_f32_16x16x32_bf16 v[68:71], v[216:219], v[224:227], v[68:71]
	v_mfma_f32_16x16x32_bf16 v[64:67], v[216:219], v[232:235], v[64:67]
	v_mfma_f32_16x16x32_bf16 v[92:95], v[190:193], v[228:231], v[92:95]
	v_mfma_f32_16x16x32_bf16 v[88:91], v[190:193], v[236:239], v[88:91]
	v_mfma_f32_16x16x32_bf16 v[84:87], v[198:201], v[228:231], v[84:87]
	v_mfma_f32_16x16x32_bf16 v[80:83], v[198:201], v[236:239], v[80:83]
	v_mfma_f32_16x16x32_bf16 v[76:79], v[212:215], v[228:231], v[76:79]
	v_mfma_f32_16x16x32_bf16 v[72:75], v[212:215], v[236:239], v[72:75]
	v_mfma_f32_16x16x32_bf16 v[68:71], v[220:223], v[228:231], v[68:71]
	v_mfma_f32_16x16x32_bf16 v[64:67], v[220:223], v[236:239], v[64:67]
	s_add_i32 m0, s100, 0x7e80
	s_barrier
	ds_read_b128 v[184:187], v152 offset:49152
	ds_read_b128 v[190:193], v152 offset:50176
	ds_read_b128 v[194:197], v151 offset:49152
	ds_read_b128 v[198:201], v151 offset:50176
	ds_read_b128 v[206:209], v150 offset:49152
	ds_read_b128 v[212:215], v150 offset:50176
	ds_read_b128 v[216:219], v149 offset:49152
	global_load_lds_dwordx4 v[248:249], off offset:384
	s_add_i32 m0, s100, 0x9e80
	ds_read_b128 v[220:223], v149 offset:50176
	global_load_lds_dwordx4 v[250:251], off offset:384
	s_barrier
	s_waitcnt lgkmcnt(0)
	v_mfma_f32_16x16x32_bf16 v[60:63], v[184:187], v[164:167], v[60:63]
	v_mfma_f32_16x16x32_bf16 v[56:59], v[184:187], v[172:175], v[56:59]
	v_mfma_f32_16x16x32_bf16 v[52:55], v[194:197], v[164:167], v[52:55]
	v_mfma_f32_16x16x32_bf16 v[48:51], v[194:197], v[172:175], v[48:51]
	v_mfma_f32_16x16x32_bf16 v[44:47], v[206:209], v[164:167], v[44:47]
	v_mfma_f32_16x16x32_bf16 v[40:43], v[206:209], v[172:175], v[40:43]
	v_mfma_f32_16x16x32_bf16 v[36:39], v[216:219], v[164:167], v[36:39]
	v_mfma_f32_16x16x32_bf16 v[32:35], v[216:219], v[172:175], v[32:35]
	v_mfma_f32_16x16x32_bf16 v[60:63], v[190:193], v[168:171], v[60:63]
	v_mfma_f32_16x16x32_bf16 v[56:59], v[190:193], v[176:179], v[56:59]
	v_mfma_f32_16x16x32_bf16 v[52:55], v[198:201], v[168:171], v[52:55]
	v_mfma_f32_16x16x32_bf16 v[48:51], v[198:201], v[176:179], v[48:51]
	v_mfma_f32_16x16x32_bf16 v[44:47], v[212:215], v[168:171], v[44:47]
	v_mfma_f32_16x16x32_bf16 v[40:43], v[212:215], v[176:179], v[40:43]
	v_mfma_f32_16x16x32_bf16 v[36:39], v[220:223], v[168:171], v[36:39]
	v_mfma_f32_16x16x32_bf16 v[32:35], v[220:223], v[176:179], v[32:35]
	s_add_i32 m0, s101, 0x1be80
	s_barrier
	global_load_lds_dwordx4 v[252:253], off offset:384
	s_add_i32 m0, m0, 0x2000
	s_add_u32 s6, s6, 0x100
	s_addc_u32 s7, s7, 0
	global_load_lds_dwordx4 v[188:189], off offset:384
	s_waitcnt vmcnt(6)
	s_barrier
	v_mfma_f32_16x16x32_bf16 v[28:31], v[184:187], v[224:227], v[28:31]
	v_mfma_f32_16x16x32_bf16 v[24:27], v[184:187], v[232:235], v[24:27]
	v_mfma_f32_16x16x32_bf16 v[20:23], v[194:197], v[224:227], v[20:23]
	v_mfma_f32_16x16x32_bf16 v[16:19], v[194:197], v[232:235], v[16:19]
	v_mfma_f32_16x16x32_bf16 v[12:15], v[206:209], v[224:227], v[12:15]
	v_mfma_f32_16x16x32_bf16 v[8:11], v[206:209], v[232:235], v[8:11]
	v_mfma_f32_16x16x32_bf16 v[4:7], v[216:219], v[224:227], v[4:7]
	v_mfma_f32_16x16x32_bf16 v[0:3], v[216:219], v[232:235], v[0:3]
	v_mfma_f32_16x16x32_bf16 v[28:31], v[190:193], v[228:231], v[28:31]
	v_mfma_f32_16x16x32_bf16 v[24:27], v[190:193], v[236:239], v[24:27]
	v_mfma_f32_16x16x32_bf16 v[20:23], v[198:201], v[228:231], v[20:23]
	v_mfma_f32_16x16x32_bf16 v[16:19], v[198:201], v[236:239], v[16:19]
	v_mfma_f32_16x16x32_bf16 v[12:15], v[212:215], v[228:231], v[12:15]
	v_mfma_f32_16x16x32_bf16 v[8:11], v[212:215], v[236:239], v[8:11]
	v_mfma_f32_16x16x32_bf16 v[4:7], v[220:223], v[228:231], v[4:7]
	v_mfma_f32_16x16x32_bf16 v[0:3], v[220:223], v[236:239], v[0:3]
	s_cmp_lt_u32 s11, s10
	s_barrier
	s_cbranch_scc1 .LBB0_219
	v_add_u32_e32 v161, 0xc000, v148
	v_add_u32_e32 v162, 0xe000, v148
	s_or_b32 s6, s60, 0x80
	s_mul_hi_u32 s7, s6, s15
	s_mul_i32 s10, s61, s15
	s_add_i32 s7, s7, s10
	s_mul_i32 s6, s6, s15
	s_lshl_b64 s[6:7], s[6:7], 1
	s_add_u32 s6, s4, s6
	s_addc_u32 s7, s5, s7
	s_add_i32 s36, s12, -1
	s_lshl_b64 s[4:5], s[36:37], 7
	s_add_u32 s4, s6, s4
	s_addc_u32 s5, s7, s5
	v_readfirstlane_b32 s6, v161
	v_lshl_add_u64 v[156:157], v[180:181], 1, s[4:5]
	s_mov_b32 m0, s6
	v_lshl_add_u64 v[128:129], v[128:129], 1, s[4:5]
	v_readfirstlane_b32 s4, v162
	ds_read_b128 v[130:133], v160
	ds_read_b128 v[134:137], v160 offset:1024
	ds_read_b128 v[138:141], v160 offset:2048
	ds_read_b128 v[142:145], v160 offset:3072
	ds_read_b128 v[164:167], v152
	ds_read_b128 v[168:171], v152 offset:1024
	ds_read_b128 v[172:175], v151
	ds_read_b128 v[176:179], v151 offset:1024
	ds_read_b128 v[184:187], v150
	ds_read_b128 v[190:193], v150 offset:1024
	ds_read_b128 v[194:197], v149
	ds_read_b128 v[198:201], v149 offset:1024
	global_load_lds_dwordx4 v[156:157], off
	s_mov_b32 m0, s4
	s_nop 0
	global_load_lds_dwordx4 v[128:129], off
	s_barrier
	s_waitcnt lgkmcnt(0)
	v_mfma_f32_16x16x32_bf16 v[124:127], v[164:167], v[130:133], v[124:127]
	v_mfma_f32_16x16x32_bf16 v[116:119], v[172:175], v[130:133], v[116:119]
	v_mfma_f32_16x16x32_bf16 v[108:111], v[184:187], v[130:133], v[108:111]
	v_mfma_f32_16x16x32_bf16 v[100:103], v[194:197], v[130:133], v[100:103]
	v_mfma_f32_16x16x32_bf16 v[124:127], v[168:171], v[134:137], v[124:127]
	v_mfma_f32_16x16x32_bf16 v[120:123], v[164:167], v[138:141], v[120:123]
	v_mfma_f32_16x16x32_bf16 v[116:119], v[176:179], v[134:137], v[116:119]
	v_mfma_f32_16x16x32_bf16 v[112:115], v[172:175], v[138:141], v[112:115]
	v_mfma_f32_16x16x32_bf16 v[108:111], v[190:193], v[134:137], v[108:111]
	v_mfma_f32_16x16x32_bf16 v[104:107], v[184:187], v[138:141], v[104:107]
	v_mfma_f32_16x16x32_bf16 v[100:103], v[198:201], v[134:137], v[100:103]
	v_mfma_f32_16x16x32_bf16 v[96:99], v[194:197], v[138:141], v[96:99]
	v_mfma_f32_16x16x32_bf16 v[160:163], v[168:171], v[142:145], v[120:123]
	v_mfma_f32_16x16x32_bf16 v[206:209], v[176:179], v[142:145], v[112:115]
	v_mfma_f32_16x16x32_bf16 v[212:215], v[190:193], v[142:145], v[104:107]
	v_mfma_f32_16x16x32_bf16 v[216:219], v[198:201], v[142:145], v[96:99]
	s_barrier
	s_nop 1
	ds_read_b128 v[96:99], v159
	ds_read_b128 v[104:107], v159 offset:1024
	ds_read_b128 v[112:115], v159 offset:2048
	ds_read_b128 v[120:123], v159 offset:3072
	s_barrier
	s_waitcnt lgkmcnt(0)
	v_mfma_f32_16x16x32_bf16 v[92:95], v[164:167], v[96:99], v[92:95]
	v_mfma_f32_16x16x32_bf16 v[84:87], v[172:175], v[96:99], v[84:87]
	v_mfma_f32_16x16x32_bf16 v[76:79], v[184:187], v[96:99], v[76:79]
	v_mfma_f32_16x16x32_bf16 v[68:71], v[194:197], v[96:99], v[68:71]
	v_mfma_f32_16x16x32_bf16 v[92:95], v[168:171], v[104:107], v[92:95]
	v_mfma_f32_16x16x32_bf16 v[88:91], v[164:167], v[112:115], v[88:91]
	v_mfma_f32_16x16x32_bf16 v[84:87], v[176:179], v[104:107], v[84:87]
	v_mfma_f32_16x16x32_bf16 v[80:83], v[172:175], v[112:115], v[80:83]
	v_mfma_f32_16x16x32_bf16 v[76:79], v[190:193], v[104:107], v[76:79]
	v_mfma_f32_16x16x32_bf16 v[72:75], v[184:187], v[112:115], v[72:75]
	v_mfma_f32_16x16x32_bf16 v[68:71], v[198:201], v[104:107], v[68:71]
	v_mfma_f32_16x16x32_bf16 v[64:67], v[194:197], v[112:115], v[64:67]
	v_mfma_f32_16x16x32_bf16 v[156:159], v[168:171], v[120:123], v[88:91]
	v_mfma_f32_16x16x32_bf16 v[164:167], v[176:179], v[120:123], v[80:83]
	v_mfma_f32_16x16x32_bf16 v[168:171], v[190:193], v[120:123], v[72:75]
	v_mfma_f32_16x16x32_bf16 v[172:175], v[198:201], v[120:123], v[64:67]
	s_barrier
	s_nop 1
	ds_read_b128 v[64:67], v152 offset:16384
	ds_read_b128 v[72:75], v152 offset:17408
	ds_read_b128 v[80:83], v151 offset:16384
	ds_read_b128 v[88:91], v151 offset:17408
	ds_read_b128 v[176:179], v150 offset:16384
	ds_read_b128 v[184:187], v150 offset:17408
	ds_read_b128 v[190:193], v149 offset:16384
	ds_read_b128 v[194:197], v149 offset:17408
	s_waitcnt vmcnt(4)
	s_barrier
	s_waitcnt lgkmcnt(0)
	v_mfma_f32_16x16x32_bf16 v[60:63], v[64:67], v[130:133], v[60:63]
	v_mfma_f32_16x16x32_bf16 v[52:55], v[80:83], v[130:133], v[52:55]
	v_mfma_f32_16x16x32_bf16 v[44:47], v[176:179], v[130:133], v[44:47]
	v_mfma_f32_16x16x32_bf16 v[36:39], v[190:193], v[130:133], v[36:39]
	v_mfma_f32_16x16x32_bf16 v[60:63], v[72:75], v[134:137], v[60:63]
	v_mfma_f32_16x16x32_bf16 v[56:59], v[64:67], v[138:141], v[56:59]
	v_mfma_f32_16x16x32_bf16 v[52:55], v[88:91], v[134:137], v[52:55]
	v_mfma_f32_16x16x32_bf16 v[48:51], v[80:83], v[138:141], v[48:51]
	v_mfma_f32_16x16x32_bf16 v[44:47], v[184:187], v[134:137], v[44:47]
	v_mfma_f32_16x16x32_bf16 v[40:43], v[176:179], v[138:141], v[40:43]
	v_mfma_f32_16x16x32_bf16 v[36:39], v[194:197], v[134:137], v[36:39]
	v_mfma_f32_16x16x32_bf16 v[32:35], v[190:193], v[138:141], v[32:35]
	v_mfma_f32_16x16x32_bf16 v[198:201], v[72:75], v[142:145], v[56:59]
	v_mfma_f32_16x16x32_bf16 v[220:223], v[88:91], v[142:145], v[48:51]
	v_mfma_f32_16x16x32_bf16 v[224:227], v[184:187], v[142:145], v[40:43]
	v_mfma_f32_16x16x32_bf16 v[128:131], v[194:197], v[142:145], v[32:35]
	v_mfma_f32_16x16x32_bf16 v[28:31], v[64:67], v[96:99], v[28:31]
	v_mfma_f32_16x16x32_bf16 v[20:23], v[80:83], v[96:99], v[20:23]
	v_mfma_f32_16x16x32_bf16 v[12:15], v[176:179], v[96:99], v[12:15]
	v_mfma_f32_16x16x32_bf16 v[4:7], v[190:193], v[96:99], v[4:7]
	v_mfma_f32_16x16x32_bf16 v[28:31], v[72:75], v[104:107], v[28:31]
	v_mfma_f32_16x16x32_bf16 v[24:27], v[64:67], v[112:115], v[24:27]
	v_mfma_f32_16x16x32_bf16 v[20:23], v[88:91], v[104:107], v[20:23]
	v_mfma_f32_16x16x32_bf16 v[16:19], v[80:83], v[112:115], v[16:19]
	v_mfma_f32_16x16x32_bf16 v[12:15], v[184:187], v[104:107], v[12:15]
	v_mfma_f32_16x16x32_bf16 v[8:11], v[176:179], v[112:115], v[8:11]
	v_mfma_f32_16x16x32_bf16 v[4:7], v[194:197], v[104:107], v[4:7]
	v_mfma_f32_16x16x32_bf16 v[0:3], v[190:193], v[112:115], v[0:3]
	v_mfma_f32_16x16x32_bf16 v[132:135], v[72:75], v[120:123], v[24:27]
	v_mfma_f32_16x16x32_bf16 v[136:139], v[88:91], v[120:123], v[16:19]
	v_mfma_f32_16x16x32_bf16 v[140:143], v[184:187], v[120:123], v[8:11]
	v_mfma_f32_16x16x32_bf16 v[176:179], v[194:197], v[120:123], v[0:3]
	s_barrier
	s_nop 1
	ds_read_b128 v[0:3], v155
	ds_read_b128 v[8:11], v155 offset:1024
	ds_read_b128 v[16:19], v155 offset:2048
	ds_read_b128 v[24:27], v155 offset:3072
	ds_read_b128 v[32:35], v152 offset:32768
	ds_read_b128 v[40:43], v152 offset:33792
	ds_read_b128 v[48:51], v151 offset:32768
	ds_read_b128 v[56:59], v151 offset:33792
	ds_read_b128 v[64:67], v150 offset:32768
	ds_read_b128 v[184:187], v150 offset:33792
	ds_read_b128 v[190:193], v149 offset:32768
	ds_read_b128 v[194:197], v149 offset:33792
	s_waitcnt vmcnt(2)
	s_barrier
	s_waitcnt lgkmcnt(0)
	v_mfma_f32_16x16x32_bf16 v[72:75], v[32:35], v[0:3], v[124:127]
	v_mfma_f32_16x16x32_bf16 v[120:123], v[40:43], v[8:11], v[72:75]
	v_mfma_f32_16x16x32_bf16 v[72:75], v[32:35], v[16:19], v[160:163]
	v_mfma_f32_16x16x32_bf16 v[124:127], v[40:43], v[24:27], v[72:75]
	v_mfma_f32_16x16x32_bf16 v[72:75], v[48:51], v[0:3], v[116:119]
	v_mfma_f32_16x16x32_bf16 v[112:115], v[56:59], v[8:11], v[72:75]
	v_mfma_f32_16x16x32_bf16 v[72:75], v[48:51], v[16:19], v[206:209]
	v_mfma_f32_16x16x32_bf16 v[116:119], v[56:59], v[24:27], v[72:75]
	v_mfma_f32_16x16x32_bf16 v[72:75], v[64:67], v[0:3], v[108:111]
	v_mfma_f32_16x16x32_bf16 v[104:107], v[184:187], v[8:11], v[72:75]
	v_mfma_f32_16x16x32_bf16 v[72:75], v[64:67], v[16:19], v[212:215]
	v_mfma_f32_16x16x32_bf16 v[108:111], v[184:187], v[24:27], v[72:75]
	v_mfma_f32_16x16x32_bf16 v[72:75], v[190:193], v[0:3], v[100:103]
	v_mfma_f32_16x16x32_bf16 v[96:99], v[194:197], v[8:11], v[72:75]
	v_mfma_f32_16x16x32_bf16 v[72:75], v[190:193], v[16:19], v[216:219]
	v_mfma_f32_16x16x32_bf16 v[100:103], v[194:197], v[24:27], v[72:75]
	s_barrier
	ds_read_b128 v[160:163], v153
	ds_read_b128 v[206:209], v153 offset:1024
	ds_read_b128 v[212:215], v153 offset:2048
	ds_read_b128 v[216:219], v153 offset:3072
	s_waitcnt vmcnt(0)
	s_barrier
	s_waitcnt lgkmcnt(0)
	v_mfma_f32_16x16x32_bf16 v[72:75], v[32:35], v[160:163], v[92:95]
	v_mfma_f32_16x16x32_bf16 v[32:35], v[32:35], v[212:215], v[156:159]
	v_mfma_f32_16x16x32_bf16 v[92:95], v[40:43], v[216:219], v[32:35]
	v_mfma_f32_16x16x32_bf16 v[32:35], v[48:51], v[160:163], v[84:87]
	v_mfma_f32_16x16x32_bf16 v[80:83], v[56:59], v[206:209], v[32:35]
	v_mfma_f32_16x16x32_bf16 v[32:35], v[48:51], v[212:215], v[164:167]
	v_mfma_f32_16x16x32_bf16 v[84:87], v[56:59], v[216:219], v[32:35]
	v_mfma_f32_16x16x32_bf16 v[32:35], v[64:67], v[160:163], v[76:79]
	v_mfma_f32_16x16x32_bf16 v[88:91], v[40:43], v[206:209], v[72:75]
	v_mfma_f32_16x16x32_bf16 v[72:75], v[184:187], v[206:209], v[32:35]
	v_mfma_f32_16x16x32_bf16 v[32:35], v[64:67], v[212:215], v[168:171]
	v_mfma_f32_16x16x32_bf16 v[76:79], v[184:187], v[216:219], v[32:35]
	v_mfma_f32_16x16x32_bf16 v[32:35], v[190:193], v[160:163], v[68:71]
	v_mfma_f32_16x16x32_bf16 v[64:67], v[194:197], v[206:209], v[32:35]
	v_mfma_f32_16x16x32_bf16 v[32:35], v[190:193], v[212:215], v[172:175]
	v_mfma_f32_16x16x32_bf16 v[68:71], v[194:197], v[216:219], v[32:35]
	s_barrier
	ds_read_b128 v[154:157], v152 offset:49152
	ds_read_b128 v[164:167], v152 offset:50176
	ds_read_b128 v[168:171], v151 offset:49152
	ds_read_b128 v[172:175], v151 offset:50176
	ds_read_b128 v[184:187], v150 offset:49152
	ds_read_b128 v[150:153], v150 offset:50176
	ds_read_b128 v[190:193], v149 offset:49152
	ds_read_b128 v[194:197], v149 offset:50176
	s_barrier
	s_waitcnt lgkmcnt(0)
	v_mfma_f32_16x16x32_bf16 v[32:35], v[154:157], v[0:3], v[60:63]
	v_mfma_f32_16x16x32_bf16 v[56:59], v[164:167], v[8:11], v[32:35]
	v_mfma_f32_16x16x32_bf16 v[32:35], v[154:157], v[16:19], v[198:201]
	v_mfma_f32_16x16x32_bf16 v[60:63], v[164:167], v[24:27], v[32:35]
	v_mfma_f32_16x16x32_bf16 v[32:35], v[168:171], v[0:3], v[52:55]
	v_mfma_f32_16x16x32_bf16 v[48:51], v[172:175], v[8:11], v[32:35]
	v_mfma_f32_16x16x32_bf16 v[32:35], v[168:171], v[16:19], v[220:223]
	v_mfma_f32_16x16x32_bf16 v[52:55], v[172:175], v[24:27], v[32:35]
	v_mfma_f32_16x16x32_bf16 v[32:35], v[184:187], v[0:3], v[44:47]
	v_mfma_f32_16x16x32_bf16 v[40:43], v[150:153], v[8:11], v[32:35]
	v_mfma_f32_16x16x32_bf16 v[32:35], v[184:187], v[16:19], v[224:227]
	v_mfma_f32_16x16x32_bf16 v[0:3], v[190:193], v[0:3], v[36:39]
	v_mfma_f32_16x16x32_bf16 v[44:47], v[150:153], v[24:27], v[32:35]
	v_mfma_f32_16x16x32_bf16 v[32:35], v[194:197], v[8:11], v[0:3]
	v_mfma_f32_16x16x32_bf16 v[0:3], v[190:193], v[16:19], v[128:131]
	v_mfma_f32_16x16x32_bf16 v[36:39], v[194:197], v[24:27], v[0:3]
	v_mfma_f32_16x16x32_bf16 v[0:3], v[154:157], v[160:163], v[28:31]
	v_mfma_f32_16x16x32_bf16 v[24:27], v[164:167], v[206:209], v[0:3]
	v_mfma_f32_16x16x32_bf16 v[0:3], v[154:157], v[212:215], v[132:135]
	v_mfma_f32_16x16x32_bf16 v[28:31], v[164:167], v[216:219], v[0:3]
	v_mfma_f32_16x16x32_bf16 v[0:3], v[168:171], v[160:163], v[20:23]
	v_mfma_f32_16x16x32_bf16 v[16:19], v[172:175], v[206:209], v[0:3]
	v_mfma_f32_16x16x32_bf16 v[0:3], v[168:171], v[212:215], v[136:139]
	v_mfma_f32_16x16x32_bf16 v[20:23], v[172:175], v[216:219], v[0:3]
	v_mfma_f32_16x16x32_bf16 v[0:3], v[184:187], v[160:163], v[12:15]
	v_mfma_f32_16x16x32_bf16 v[8:11], v[150:153], v[206:209], v[0:3]
	v_mfma_f32_16x16x32_bf16 v[0:3], v[184:187], v[212:215], v[140:143]
	v_mfma_f32_16x16x32_bf16 v[12:15], v[150:153], v[216:219], v[0:3]
	v_mfma_f32_16x16x32_bf16 v[0:3], v[190:193], v[160:163], v[4:7]
	v_mfma_f32_16x16x32_bf16 v[4:7], v[190:193], v[212:215], v[176:179]
	v_mfma_f32_16x16x32_bf16 v[0:3], v[194:197], v[206:209], v[0:3]
	v_mfma_f32_16x16x32_bf16 v[4:7], v[194:197], v[216:219], v[4:7]
	s_movk_i32 s4, 0x100
	v_cmp_gt_u32_e32 vcc, s4, v146
	s_barrier
	s_and_saveexec_b64 s[4:5], vcc
	s_cbranch_execz .LBB0_222
	s_barrier
